# FFN-up last (quarter-populated) round as 128 half tiles; next-layer weight conversion on the remaining 128 workgroups
# speedup vs baseline: 1.0031x; 1.0031x over previous
.LBB0_53:
	s_add_i32 s52, s52, 1
	s_mul_i32 s4, s52, s50
	s_mul_hi_u32 s5, s52, s0
	s_add_i32 s5, s5, s4
	s_mul_i32 s4, s52, s0
	v_readlane_b32 s99, v255, 41
	s_cmp_eq_u32 s52, 8
	s_cselect_b32 s99, s99, 0
	s_lshr_b32 s98, s1, s99
	s_add_u32 s10, s4, s98
	s_addc_u32 s11, s5, s51
	v_mov_b64_e32 v[2:3], 0x83f
	v_cmp_gt_i64_e64 s[4:5], s[10:11], v[2:3]
	s_mov_b64 s[6:7], s[34:35]
	s_mov_b64 s[8:9], s[30:31]
	s_mov_b32 s12, s24
	s_mov_b32 s13, s22
	s_and_b64 vcc, exec, s[4:5]
	s_cbranch_vccnz .LBB0_55
	s_ashr_i32 s14, s10, 31
	s_lshr_b32 s14, s14, 29
	s_add_i32 s14, s10, s14
	s_ashr_i32 s15, s14, 3
	s_and_b32 s14, s14, -8
	s_sub_i32 s14, s10, s14
	s_cmp_lt_i32 s14, 0
	s_movk_i32 s16, 0x109
	s_cselect_b32 s16, s16, 0x108
	s_mul_i32 s14, s16, s14
	s_add_i32 s14, s14, s15
	s_mul_hi_i32 s15, s14, 0x2e8ba2e9
	s_lshr_b32 s16, s15, 31
	s_ashr_i32 s15, s15, 4
	s_add_i32 s15, s15, s16
	s_lshl_b32 s16, s15, 2
	s_sub_i32 s17, 0x60, s16
	s_min_i32 s17, s17, 4
	s_abs_i32 s22, s17
	v_cvt_f32_u32_e32 v0, s22
	s_sub_i32 s24, 0, s22
	s_mulk_i32 s15, 0x58
	s_sub_i32 s14, s14, s15
	v_rcp_iflag_f32_e32 v0, v0
	s_abs_i32 s15, s14
	s_xor_b32 s23, s14, s17
	s_ashr_i32 s23, s23, 31
	v_mul_f32_e32 v0, 0x4f7ffffe, v0
	v_cvt_u32_f32_e32 v0, v0
	s_nop 0
	v_readfirstlane_b32 s25, v0
	s_mul_i32 s24, s24, s25
	s_mul_hi_u32 s24, s25, s24
	s_add_i32 s25, s25, s24
	s_mul_hi_u32 s24, s15, s25
	s_mul_i32 s25, s24, s22
	s_sub_i32 s15, s15, s25
	s_add_i32 s30, s24, 1
	s_sub_i32 s25, s15, s22
	s_cmp_ge_u32 s15, s22
	s_cselect_b32 s24, s30, s24
	s_cselect_b32 s15, s25, s15
	s_add_i32 s25, s24, 1
	s_cmp_ge_u32 s15, s22
	s_cselect_b32 s15, s25, s24
	s_xor_b32 s15, s15, s23
	s_sub_i32 s22, s15, s23
	s_mul_i32 s15, s22, s17
	s_sub_i32 s14, s14, s15
	s_add_i32 s24, s14, s16
.LBB0_55:
	v_mov_b64_e32 v[2:3], 0x840
	s_ashr_i32 s25, s24, 31
	v_cmp_lt_i64_e32 vcc, s[10:11], v[2:3]
	s_lshl_b64 s[10:11], s[24:25], 19
	v_readlane_b32 s14, v254, 33
	v_readlane_b32 s15, v254, 34
	s_add_u32 s34, s14, s10
	s_addc_u32 s35, s15, s11
	v_readlane_b32 s98, v254, 0
	s_and_b32 s98, s98, s99
	s_mul_i32 s98, s98, 0x40000
	s_add_u32 s34, s34, s98
	s_addc_u32 s35, s35, 0
	s_and_b64 s[10:11], vcc, exec
	s_cselect_b32 s14, s35, s7
	s_cselect_b32 s15, s34, s6
	s_ashr_i32 s23, s22, 31
	s_lshl_b64 s[10:11], s[22:23], 19
	s_add_u32 s30, s3, s10
	s_addc_u32 s31, s42, s11
	s_and_b64 s[10:11], vcc, exec
	s_cselect_b32 s16, s31, s9
	s_cselect_b32 s17, s30, s8
	s_add_u32 s23, s8, 0x100
	s_addc_u32 s25, s9, 0
	s_add_u32 s6, s6, 0x40080
	v_mov_b32_e32 v2, 0
	s_addc_u32 s7, s7, 0
	s_mov_b32 s40, -2
	v_mov_b32_e32 v3, v2
	v_mov_b32_e32 v4, v2
	v_mov_b32_e32 v5, v2
	v_mov_b32_e32 v6, v2
	v_mov_b32_e32 v7, v2
	v_mov_b32_e32 v8, v2
	v_mov_b32_e32 v9, v2
	v_mov_b32_e32 v18, v2
	v_mov_b32_e32 v19, v2
	v_mov_b32_e32 v20, v2
	v_mov_b32_e32 v21, v2
	v_mov_b32_e32 v22, v2
	v_mov_b32_e32 v23, v2
	v_mov_b32_e32 v24, v2
	v_mov_b32_e32 v25, v2
	v_mov_b32_e32 v30, v2
	v_mov_b32_e32 v31, v2
	v_mov_b32_e32 v32, v2
	v_mov_b32_e32 v33, v2
	v_mov_b32_e32 v38, v2
	v_mov_b32_e32 v39, v2
	v_mov_b32_e32 v40, v2
	v_mov_b32_e32 v41, v2
	v_mov_b32_e32 v46, v2
	v_mov_b32_e32 v47, v2
	v_mov_b32_e32 v48, v2
	v_mov_b32_e32 v49, v2
	v_mov_b32_e32 v54, v2
	v_mov_b32_e32 v55, v2
	v_mov_b32_e32 v56, v2
	v_mov_b32_e32 v57, v2
	v_mov_b32_e32 v10, v2
	v_mov_b32_e32 v11, v2
	v_mov_b32_e32 v12, v2
	v_mov_b32_e32 v13, v2
	v_mov_b32_e32 v14, v2
	v_mov_b32_e32 v15, v2
	v_mov_b32_e32 v16, v2
	v_mov_b32_e32 v17, v2
	v_mov_b32_e32 v26, v2
	v_mov_b32_e32 v27, v2
	v_mov_b32_e32 v28, v2
	v_mov_b32_e32 v29, v2
	v_mov_b32_e32 v34, v2
	v_mov_b32_e32 v35, v2
	v_mov_b32_e32 v36, v2
	v_mov_b32_e32 v37, v2
	v_mov_b32_e32 v42, v2
	v_mov_b32_e32 v43, v2
	v_mov_b32_e32 v44, v2
	v_mov_b32_e32 v45, v2
	v_mov_b32_e32 v50, v2
	v_mov_b32_e32 v51, v2
	v_mov_b32_e32 v52, v2
	v_mov_b32_e32 v53, v2
	v_mov_b32_e32 v58, v2
	v_mov_b32_e32 v59, v2
	v_mov_b32_e32 v60, v2
	v_mov_b32_e32 v61, v2
	v_mov_b32_e32 v62, v2
	v_mov_b32_e32 v63, v2
	v_mov_b32_e32 v64, v2
	v_mov_b32_e32 v65, v2
	v_mov_b32_e32 v98, v2
	v_mov_b32_e32 v99, v2
	v_mov_b32_e32 v100, v2
	v_mov_b32_e32 v101, v2
	v_mov_b32_e32 v102, v2
	v_mov_b32_e32 v103, v2
	v_mov_b32_e32 v104, v2
	v_mov_b32_e32 v105, v2
	v_mov_b32_e32 v114, v2
	v_mov_b32_e32 v115, v2
	v_mov_b32_e32 v116, v2
	v_mov_b32_e32 v117, v2
	v_mov_b32_e32 v118, v2
	v_mov_b32_e32 v119, v2
	v_mov_b32_e32 v120, v2
	v_mov_b32_e32 v121, v2
	v_mov_b32_e32 v126, v2
	v_mov_b32_e32 v127, v2
	v_mov_b32_e32 v128, v2
	v_mov_b32_e32 v129, v2
	v_mov_b32_e32 v134, v2
	v_mov_b32_e32 v135, v2
	v_mov_b32_e32 v136, v2
	v_mov_b32_e32 v137, v2
	v_mov_b32_e32 v142, v2
	v_mov_b32_e32 v143, v2
	v_mov_b32_e32 v144, v2
	v_mov_b32_e32 v145, v2
	v_mov_b32_e32 v150, v2
	v_mov_b32_e32 v151, v2
	v_mov_b32_e32 v152, v2
	v_mov_b32_e32 v153, v2
	v_mov_b32_e32 v106, v2
	v_mov_b32_e32 v107, v2
	v_mov_b32_e32 v108, v2
	v_mov_b32_e32 v109, v2
	v_mov_b32_e32 v110, v2
	v_mov_b32_e32 v111, v2
	v_mov_b32_e32 v112, v2
	v_mov_b32_e32 v113, v2
	v_mov_b32_e32 v122, v2
	v_mov_b32_e32 v123, v2
	v_mov_b32_e32 v124, v2
	v_mov_b32_e32 v125, v2
	v_mov_b32_e32 v130, v2
	v_mov_b32_e32 v131, v2
	v_mov_b32_e32 v132, v2
	v_mov_b32_e32 v133, v2
	v_mov_b32_e32 v138, v2
	v_mov_b32_e32 v139, v2
	v_mov_b32_e32 v140, v2
	v_mov_b32_e32 v141, v2
	v_mov_b32_e32 v146, v2
	v_mov_b32_e32 v147, v2
	v_mov_b32_e32 v148, v2
	v_mov_b32_e32 v149, v2
	v_mov_b32_e32 v154, v2
	v_mov_b32_e32 v155, v2
	v_mov_b32_e32 v156, v2
	v_mov_b32_e32 v157, v2
	v_mov_b32_e32 v158, v2
	v_mov_b32_e32 v159, v2
	v_mov_b32_e32 v160, v2
	v_mov_b32_e32 v161, v2
	v_readlane_b32 s99, v255, 41
	s_cmp_eq_u32 s52, 9
	s_cselect_b32 s99, s99, 0
.LBB0_56:
	s_add_u32 s8, s6, 0xfffc0080
	s_addc_u32 s9, s7, -1
	s_add_i32 s41, 0, 0x10000
	v_add_u32_e32 v0, s41, v169
	ds_read_b128 v[66:69], v0
	ds_read_b128 v[70:73], v0 offset:1024
	ds_read_b128 v[74:77], v0 offset:2048
	ds_read_b128 v[78:81], v0 offset:3072
	s_cmp_eq_u32 s40, 12
	s_cselect_b32 s11, s14, s9
	s_cselect_b32 s10, s15, s8
	s_cselect_b32 s9, s16, s25
	s_cselect_b32 s8, s17, s23
	v_lshl_add_u64 v[200:201], s[6:7], 0, v[182:183]
	s_add_i32 m0, s44, 0xc000
	ds_read_b128 v[82:85], v229
	ds_read_b128 v[86:89], v229 offset:1024
	ds_read_b128 v[90:93], v229 offset:2048
	ds_read_b128 v[94:97], v229 offset:3072
	ds_read_b128 v[184:187], v229 offset:4096
	ds_read_b128 v[188:191], v229 offset:5120
	ds_read_b128 v[192:195], v229 offset:6144
	ds_read_b128 v[196:199], v229 offset:7168
	global_load_lds_dwordx4 v[200:201], off
	v_lshl_add_u64 v[200:201], s[6:7], 0, v[180:181]
	s_add_i32 m0, s44, 0xe000
	s_nop 0
	global_load_lds_dwordx4 v[200:201], off
	s_waitcnt lgkmcnt(8)
	s_barrier
	s_waitcnt lgkmcnt(0)
	s_setprio 1
	s_waitcnt lgkmcnt(0)
	v_mfma_f32_16x16x32_bf16 v[158:161], v[66:69], v[82:85], v[158:161]
	v_mfma_f32_16x16x32_bf16 v[154:157], v[74:77], v[82:85], v[154:157]
	v_mfma_f32_16x16x32_bf16 v[146:149], v[66:69], v[90:93], v[146:149]
	v_mfma_f32_16x16x32_bf16 v[138:141], v[74:77], v[90:93], v[138:141]
	v_mfma_f32_16x16x32_bf16 v[130:133], v[66:69], v[184:187], v[130:133]
	v_mfma_f32_16x16x32_bf16 v[122:125], v[74:77], v[184:187], v[122:125]
	v_mfma_f32_16x16x32_bf16 v[110:113], v[66:69], v[192:195], v[110:113]
	v_mfma_f32_16x16x32_bf16 v[106:109], v[74:77], v[192:195], v[106:109]
	v_mfma_f32_16x16x32_bf16 v[158:161], v[70:73], v[86:89], v[158:161]
	v_mfma_f32_16x16x32_bf16 v[154:157], v[78:81], v[86:89], v[154:157]
	v_mfma_f32_16x16x32_bf16 v[146:149], v[70:73], v[94:97], v[146:149]
	v_mfma_f32_16x16x32_bf16 v[138:141], v[78:81], v[94:97], v[138:141]
	v_mfma_f32_16x16x32_bf16 v[130:133], v[70:73], v[188:191], v[130:133]
	v_mfma_f32_16x16x32_bf16 v[122:125], v[78:81], v[188:191], v[122:125]
	v_mfma_f32_16x16x32_bf16 v[110:113], v[70:73], v[196:199], v[110:113]
	v_mfma_f32_16x16x32_bf16 v[106:109], v[78:81], v[196:199], v[106:109]
	s_setprio 0
	s_barrier
	s_add_i32 s53, 0, 0x14000
	s_add_i32 s41, s41, s43
	v_add_u32_e32 v0, s53, v169
	v_lshl_add_u64 v[200:201], s[8:9], 0, v[176:177]
	s_mov_b32 m0, s41
	ds_read_b128 v[230:233], v0
	ds_read_b128 v[234:237], v0 offset:1024
	ds_read_b128 v[238:241], v0 offset:2048
	ds_read_b128 v[242:245], v0 offset:3072
	global_load_lds_dwordx4 v[200:201], off
	v_lshl_add_u64 v[210:211], s[8:9], 0, v[178:179]
	s_add_i32 m0, s41, 0x2000
	s_nop 0
	global_load_lds_dwordx4 v[210:211], off
	s_barrier
	s_waitcnt lgkmcnt(0)
	s_setprio 1
	s_waitcnt lgkmcnt(0)
	v_mfma_f32_16x16x32_bf16 v[150:153], v[230:233], v[82:85], v[150:153]
	v_mfma_f32_16x16x32_bf16 v[82:85], v[238:241], v[82:85], v[142:145]
	v_mfma_f32_16x16x32_bf16 v[150:153], v[234:237], v[86:89], v[150:153]
	v_mfma_f32_16x16x32_bf16 v[82:85], v[242:245], v[86:89], v[82:85]
	v_mfma_f32_16x16x32_bf16 v[86:89], v[230:233], v[90:93], v[134:137]
	v_mfma_f32_16x16x32_bf16 v[90:93], v[238:241], v[90:93], v[126:129]
	v_mfma_f32_16x16x32_bf16 v[114:117], v[238:241], v[184:187], v[114:117]
	v_mfma_f32_16x16x32_bf16 v[102:105], v[230:233], v[192:195], v[102:105]
	v_mfma_f32_16x16x32_bf16 v[98:101], v[238:241], v[192:195], v[98:101]
	v_mfma_f32_16x16x32_bf16 v[86:89], v[234:237], v[94:97], v[86:89]
	v_mfma_f32_16x16x32_bf16 v[90:93], v[242:245], v[94:97], v[90:93]
	v_mfma_f32_16x16x32_bf16 v[94:97], v[230:233], v[184:187], v[118:121]
	v_mfma_f32_16x16x32_bf16 v[114:117], v[242:245], v[188:191], v[114:117]
	v_mfma_f32_16x16x32_bf16 v[102:105], v[234:237], v[196:199], v[102:105]
	v_mfma_f32_16x16x32_bf16 v[98:101], v[242:245], v[196:199], v[98:101]
	v_mfma_f32_16x16x32_bf16 v[94:97], v[234:237], v[188:191], v[94:97]
	s_setprio 0
	s_mov_b32 m0, s44
	v_lshl_add_u64 v[172:173], s[10:11], 0, v[176:177]
	s_barrier
	ds_read_b128 v[118:121], v229 offset:16384
	ds_read_b128 v[126:129], v229 offset:17408
	ds_read_b128 v[134:137], v229 offset:18432
	ds_read_b128 v[142:145], v229 offset:19456
	ds_read_b128 v[184:187], v229 offset:20480
	ds_read_b128 v[188:191], v229 offset:21504
	ds_read_b128 v[192:195], v229 offset:22528
	ds_read_b128 v[196:199], v229 offset:23552
	global_load_lds_dwordx4 v[172:173], off
	v_lshl_add_u64 v[174:175], s[10:11], 0, v[178:179]
	s_mov_b32 m0, s45
	s_nop 0
	global_load_lds_dwordx4 v[174:175], off
	s_barrier
	s_waitcnt lgkmcnt(0)
	s_setprio 1
	s_waitcnt lgkmcnt(0)
	s_cmp_lg_u32 s99, 0
	s_cbranch_scc1 .Lfu_skip3
	v_mfma_f32_16x16x32_bf16 v[62:65], v[66:69], v[118:121], v[62:65]
	v_mfma_f32_16x16x32_bf16 v[58:61], v[74:77], v[118:121], v[58:61]
	v_mfma_f32_16x16x32_bf16 v[50:53], v[66:69], v[134:137], v[50:53]
	v_mfma_f32_16x16x32_bf16 v[42:45], v[74:77], v[134:137], v[42:45]
	v_mfma_f32_16x16x32_bf16 v[34:37], v[66:69], v[184:187], v[34:37]
	v_mfma_f32_16x16x32_bf16 v[26:29], v[74:77], v[184:187], v[26:29]
	v_mfma_f32_16x16x32_bf16 v[14:17], v[66:69], v[192:195], v[14:17]
	v_mfma_f32_16x16x32_bf16 v[10:13], v[74:77], v[192:195], v[10:13]
	v_mfma_f32_16x16x32_bf16 v[62:65], v[70:73], v[126:129], v[62:65]
	v_mfma_f32_16x16x32_bf16 v[58:61], v[78:81], v[126:129], v[58:61]
	v_mfma_f32_16x16x32_bf16 v[50:53], v[70:73], v[142:145], v[50:53]
	v_mfma_f32_16x16x32_bf16 v[42:45], v[78:81], v[142:145], v[42:45]
	v_mfma_f32_16x16x32_bf16 v[34:37], v[70:73], v[188:191], v[34:37]
	v_mfma_f32_16x16x32_bf16 v[26:29], v[78:81], v[188:191], v[26:29]
	v_mfma_f32_16x16x32_bf16 v[14:17], v[70:73], v[196:199], v[14:17]
	v_mfma_f32_16x16x32_bf16 v[10:13], v[78:81], v[196:199], v[10:13]
.Lfu_skip3:
	s_setprio 0
	s_barrier
	s_add_u32 s54, s8, 0x40000
	s_addc_u32 s55, s9, 0
	s_add_i32 s41, s53, s43
	v_lshl_add_u64 v[66:67], s[54:55], 0, v[176:177]
	s_mov_b32 m0, s41
	s_nop 0
	global_load_lds_dwordx4 v[66:67], off
	v_lshl_add_u64 v[66:67], s[54:55], 0, v[178:179]
	s_add_i32 m0, s41, 0x2000
	s_nop 0
	global_load_lds_dwordx4 v[66:67], off
	s_waitcnt vmcnt(6)
	s_barrier
	s_setprio 1
	s_cmp_lg_u32 s99, 0
	s_cbranch_scc1 .Lfu_skip4
	v_mfma_f32_16x16x32_bf16 v[54:57], v[230:233], v[118:121], v[54:57]
	v_mfma_f32_16x16x32_bf16 v[46:49], v[238:241], v[118:121], v[46:49]
	v_mfma_f32_16x16x32_bf16 v[38:41], v[230:233], v[134:137], v[38:41]
	v_mfma_f32_16x16x32_bf16 v[30:33], v[238:241], v[134:137], v[30:33]
	v_mfma_f32_16x16x32_bf16 v[22:25], v[230:233], v[184:187], v[22:25]
	v_mfma_f32_16x16x32_bf16 v[18:21], v[238:241], v[184:187], v[18:21]
	v_mfma_f32_16x16x32_bf16 v[6:9], v[230:233], v[192:195], v[6:9]
	v_mfma_f32_16x16x32_bf16 v[2:5], v[238:241], v[192:195], v[2:5]
	v_mfma_f32_16x16x32_bf16 v[54:57], v[234:237], v[126:129], v[54:57]
	v_mfma_f32_16x16x32_bf16 v[46:49], v[242:245], v[126:129], v[46:49]
	v_mfma_f32_16x16x32_bf16 v[38:41], v[234:237], v[142:145], v[38:41]
	v_mfma_f32_16x16x32_bf16 v[30:33], v[242:245], v[142:145], v[30:33]
	v_mfma_f32_16x16x32_bf16 v[22:25], v[234:237], v[188:191], v[22:25]
	v_mfma_f32_16x16x32_bf16 v[18:21], v[242:245], v[188:191], v[18:21]
	v_mfma_f32_16x16x32_bf16 v[6:9], v[234:237], v[196:199], v[6:9]
	v_mfma_f32_16x16x32_bf16 v[2:5], v[242:245], v[196:199], v[2:5]
.Lfu_skip4:
	s_setprio 0
	s_add_i32 s41, 0, 0x18000
	v_add_u32_e32 v0, s41, v169
	s_barrier
	ds_read_b128 v[66:69], v0
	ds_read_b128 v[70:73], v0 offset:1024
	ds_read_b128 v[74:77], v0 offset:2048
	ds_read_b128 v[78:81], v0 offset:3072
	s_add_u32 s10, s10, 0x40000
	s_addc_u32 s11, s11, 0
	s_mov_b32 m0, s46
	v_lshl_add_u64 v[134:135], s[10:11], 0, v[176:177]
	ds_read_b128 v[118:121], v229 offset:32768
	ds_read_b128 v[126:129], v229 offset:33792
	ds_read_b128 v[184:187], v229 offset:34816
	ds_read_b128 v[188:191], v229 offset:35840
	ds_read_b128 v[192:195], v229 offset:36864
	ds_read_b128 v[196:199], v229 offset:37888
	ds_read_b128 v[230:233], v229 offset:38912
	ds_read_b128 v[234:237], v229 offset:39936
	global_load_lds_dwordx4 v[134:135], off
	v_lshl_add_u64 v[134:135], s[10:11], 0, v[178:179]
	s_mov_b32 m0, s47
	s_nop 0
	global_load_lds_dwordx4 v[134:135], off
	s_waitcnt lgkmcnt(8)
	s_barrier
	s_waitcnt lgkmcnt(0)
	s_setprio 1
	s_waitcnt lgkmcnt(0)
	v_mfma_f32_16x16x32_bf16 v[134:137], v[66:69], v[118:121], v[158:161]
	v_mfma_f32_16x16x32_bf16 v[158:161], v[70:73], v[126:129], v[134:137]
	v_mfma_f32_16x16x32_bf16 v[134:137], v[74:77], v[118:121], v[154:157]
	v_mfma_f32_16x16x32_bf16 v[154:157], v[78:81], v[126:129], v[134:137]
	v_mfma_f32_16x16x32_bf16 v[134:137], v[66:69], v[184:187], v[146:149]
	v_mfma_f32_16x16x32_bf16 v[146:149], v[70:73], v[188:191], v[134:137]
	v_mfma_f32_16x16x32_bf16 v[134:137], v[74:77], v[184:187], v[138:141]
	v_mfma_f32_16x16x32_bf16 v[130:133], v[66:69], v[192:195], v[130:133]
	v_mfma_f32_16x16x32_bf16 v[122:125], v[74:77], v[192:195], v[122:125]
	v_mfma_f32_16x16x32_bf16 v[110:113], v[66:69], v[230:233], v[110:113]
	v_mfma_f32_16x16x32_bf16 v[106:109], v[74:77], v[230:233], v[106:109]
	v_mfma_f32_16x16x32_bf16 v[138:141], v[78:81], v[188:191], v[134:137]
	v_mfma_f32_16x16x32_bf16 v[130:133], v[70:73], v[196:199], v[130:133]
	v_mfma_f32_16x16x32_bf16 v[122:125], v[78:81], v[196:199], v[122:125]
	v_mfma_f32_16x16x32_bf16 v[110:113], v[70:73], v[234:237], v[110:113]
	v_mfma_f32_16x16x32_bf16 v[106:109], v[78:81], v[234:237], v[106:109]
	s_setprio 0
	s_barrier
	s_add_i32 s10, 0, 0x1c000
	s_add_i32 s11, s41, s43
	v_add_u32_e32 v0, s10, v169
	v_lshl_add_u64 v[134:135], v[200:201], 0, s[92:93]
	s_mov_b32 m0, s11
	ds_read_b128 v[238:241], v0
	ds_read_b128 v[242:245], v0 offset:1024
	ds_read_b128 v[246:249], v0 offset:2048
	ds_read_b128 v[250:253], v0 offset:3072
	global_load_lds_dwordx4 v[134:135], off
	v_lshl_add_u64 v[134:135], v[210:211], 0, s[92:93]
	s_add_i32 m0, s11, 0x2000
	s_nop 0
	global_load_lds_dwordx4 v[134:135], off
	s_barrier
	s_waitcnt lgkmcnt(0)
	s_setprio 1
	s_waitcnt lgkmcnt(0)
	v_mfma_f32_16x16x32_bf16 v[82:85], v[246:249], v[118:121], v[82:85]
	v_mfma_f32_16x16x32_bf16 v[134:137], v[238:241], v[118:121], v[150:153]
	v_mfma_f32_16x16x32_bf16 v[142:145], v[250:253], v[126:129], v[82:85]
	v_mfma_f32_16x16x32_bf16 v[82:85], v[238:241], v[184:187], v[86:89]
	v_mfma_f32_16x16x32_bf16 v[150:153], v[242:245], v[126:129], v[134:137]
	v_mfma_f32_16x16x32_bf16 v[134:137], v[242:245], v[188:191], v[82:85]
	v_mfma_f32_16x16x32_bf16 v[82:85], v[246:249], v[184:187], v[90:93]
	v_mfma_f32_16x16x32_bf16 v[126:129], v[250:253], v[188:191], v[82:85]
	v_mfma_f32_16x16x32_bf16 v[82:85], v[238:241], v[192:195], v[94:97]
	v_mfma_f32_16x16x32_bf16 v[118:121], v[242:245], v[196:199], v[82:85]
	v_mfma_f32_16x16x32_bf16 v[82:85], v[246:249], v[192:195], v[114:117]
	v_mfma_f32_16x16x32_bf16 v[114:117], v[250:253], v[196:199], v[82:85]
	v_mfma_f32_16x16x32_bf16 v[82:85], v[238:241], v[230:233], v[102:105]
	v_mfma_f32_16x16x32_bf16 v[102:105], v[242:245], v[234:237], v[82:85]
	v_mfma_f32_16x16x32_bf16 v[82:85], v[246:249], v[230:233], v[98:101]
	v_mfma_f32_16x16x32_bf16 v[98:101], v[250:253], v[234:237], v[82:85]
	s_setprio 0
	s_mov_b32 m0, s48
	v_lshl_add_u64 v[172:173], v[172:173], 0, s[92:93]
	s_barrier
	s_nop 2
	ds_read_b128 v[82:85], v229 offset:49152
	ds_read_b128 v[86:89], v229 offset:50176
	ds_read_b128 v[90:93], v229 offset:51200
	ds_read_b128 v[94:97], v229 offset:52224
	ds_read_b128 v[184:187], v229 offset:53248
	ds_read_b128 v[188:191], v229 offset:54272
	ds_read_b128 v[192:195], v229 offset:55296
	ds_read_b128 v[196:199], v229 offset:56320
	global_load_lds_dwordx4 v[172:173], off
	v_lshl_add_u64 v[172:173], v[174:175], 0, s[92:93]
	s_mov_b32 m0, s49
	s_nop 0
	global_load_lds_dwordx4 v[172:173], off
	s_barrier
	s_waitcnt lgkmcnt(0)
	s_setprio 1
	s_waitcnt lgkmcnt(0)
	s_cmp_lg_u32 s99, 0
	s_cbranch_scc1 .Lfu_skip7
	v_mfma_f32_16x16x32_bf16 v[62:65], v[66:69], v[82:85], v[62:65]
	v_mfma_f32_16x16x32_bf16 v[58:61], v[74:77], v[82:85], v[58:61]
	v_mfma_f32_16x16x32_bf16 v[50:53], v[66:69], v[90:93], v[50:53]
	v_mfma_f32_16x16x32_bf16 v[42:45], v[74:77], v[90:93], v[42:45]
	v_mfma_f32_16x16x32_bf16 v[34:37], v[66:69], v[184:187], v[34:37]
	v_mfma_f32_16x16x32_bf16 v[26:29], v[74:77], v[184:187], v[26:29]
	v_mfma_f32_16x16x32_bf16 v[14:17], v[66:69], v[192:195], v[14:17]
	v_mfma_f32_16x16x32_bf16 v[10:13], v[74:77], v[192:195], v[10:13]
	v_mfma_f32_16x16x32_bf16 v[62:65], v[70:73], v[86:89], v[62:65]
	v_mfma_f32_16x16x32_bf16 v[58:61], v[78:81], v[86:89], v[58:61]
	v_mfma_f32_16x16x32_bf16 v[50:53], v[70:73], v[94:97], v[50:53]
	v_mfma_f32_16x16x32_bf16 v[42:45], v[78:81], v[94:97], v[42:45]
	v_mfma_f32_16x16x32_bf16 v[34:37], v[70:73], v[188:191], v[34:37]
	v_mfma_f32_16x16x32_bf16 v[26:29], v[78:81], v[188:191], v[26:29]
	v_mfma_f32_16x16x32_bf16 v[14:17], v[70:73], v[196:199], v[14:17]
	v_mfma_f32_16x16x32_bf16 v[10:13], v[78:81], v[196:199], v[10:13]
.Lfu_skip7:
	s_setprio 0
	s_barrier
	s_add_u32 s8, s8, 0x40080
	s_addc_u32 s9, s9, 0
	s_add_i32 s10, s10, s43
	v_lshl_add_u64 v[66:67], s[8:9], 0, v[176:177]
	s_mov_b32 m0, s10
	s_nop 0
	global_load_lds_dwordx4 v[66:67], off
	v_lshl_add_u64 v[66:67], s[8:9], 0, v[178:179]
	s_add_i32 m0, s10, 0x2000
	s_nop 0
	global_load_lds_dwordx4 v[66:67], off
	s_waitcnt vmcnt(6)
	s_barrier
	s_setprio 1
	s_cmp_lg_u32 s99, 0
	s_cbranch_scc1 .Lfu_skip8
	v_mfma_f32_16x16x32_bf16 v[54:57], v[238:241], v[82:85], v[54:57]
	v_mfma_f32_16x16x32_bf16 v[46:49], v[246:249], v[82:85], v[46:49]
	v_mfma_f32_16x16x32_bf16 v[38:41], v[238:241], v[90:93], v[38:41]
	v_mfma_f32_16x16x32_bf16 v[30:33], v[246:249], v[90:93], v[30:33]
	v_mfma_f32_16x16x32_bf16 v[22:25], v[238:241], v[184:187], v[22:25]
	v_mfma_f32_16x16x32_bf16 v[18:21], v[246:249], v[184:187], v[18:21]
	v_mfma_f32_16x16x32_bf16 v[6:9], v[238:241], v[192:195], v[6:9]
	v_mfma_f32_16x16x32_bf16 v[2:5], v[246:249], v[192:195], v[2:5]
	v_mfma_f32_16x16x32_bf16 v[54:57], v[242:245], v[86:89], v[54:57]
	v_mfma_f32_16x16x32_bf16 v[46:49], v[250:253], v[86:89], v[46:49]
	v_mfma_f32_16x16x32_bf16 v[38:41], v[242:245], v[94:97], v[38:41]
	v_mfma_f32_16x16x32_bf16 v[30:33], v[250:253], v[94:97], v[30:33]
	v_mfma_f32_16x16x32_bf16 v[22:25], v[242:245], v[188:191], v[22:25]
	v_mfma_f32_16x16x32_bf16 v[18:21], v[250:253], v[188:191], v[18:21]
	v_mfma_f32_16x16x32_bf16 v[6:9], v[242:245], v[196:199], v[6:9]
	v_mfma_f32_16x16x32_bf16 v[2:5], v[250:253], v[196:199], v[2:5]
.Lfu_skip8:
	s_setprio 0
	s_add_i32 s40, s40, 2
	s_add_u32 s23, s23, 0x100
	s_addc_u32 s25, s25, 0
	s_add_u32 s6, s6, 0x100
	s_addc_u32 s7, s7, 0
	s_cmp_gt_u32 s40, 13
	s_barrier
	s_cbranch_scc0 .LBB0_56
	v_mov_b32_e32 v0, v163
	v_mov_b32_e32 v186, v1
	v_lshrrev_b32_e32 v66, 1, v0
	v_and_b32_e32 v66, 0x78, v66
	v_lshl_or_b32 v184, s13, 7, v66
	v_ashrrev_i32_e32 v185, 31, v184
	v_lshlrev_b64 v[66:67], 2, v[184:185]
	v_lshl_add_u64 v[70:71], s[26:27], 0, v[66:67]
	v_lshl_add_u64 v[74:75], s[36:37], 0, v[66:67]
	v_lshl_add_u64 v[78:79], s[38:39], 0, v[66:67]
	v_lshl_add_u64 v[94:95], s[28:29], 0, v[66:67]
	global_load_dwordx4 v[66:69], v[70:71], off offset:16
	global_load_dwordx4 v[82:85], v[70:71], off
	s_nop 0
	global_load_dwordx4 v[70:73], v[74:75], off offset:16
	global_load_dwordx4 v[86:89], v[74:75], off
	s_nop 0
	global_load_dwordx4 v[74:77], v[78:79], off offset:16
	global_load_dwordx4 v[90:93], v[78:79], off
	s_nop 0
	global_load_dwordx4 v[78:81], v[94:95], off offset:16
	s_nop 0
	global_load_dwordx4 v[94:97], v[94:95], off
	v_and_b32_e32 v230, 15, v0
	v_ashrrev_i32_e32 v0, 2, v0
	v_and_b32_e32 v0, 0xffffffc0, v0
	v_mov_b32_e32 v187, v1
	v_mov_b32_e32 v194, v1
	v_mov_b32_e32 v195, v1
	v_mov_b32_e32 v198, v1
	v_mov_b32_e32 v199, v1
	v_mov_b32_e32 v190, v1
	v_mov_b32_e32 v191, v1
	v_lshl_add_u32 v231, s12, 8, v0
	v_readlane_b32 s98, v254, 0
	s_and_b32 s98, s98, s99
	s_lshl_b32 s98, s98, 7
	v_add_u32_e32 v231, s98, v231
	v_mov_b32_dpp v186, v134 row_ror:15 row_mask:0xf bank_mask:0xf
	v_mov_b32_e32 v188, v1
	v_mov_b32_dpp v187, v135 row_ror:15 row_mask:0xf bank_mask:0xf
	v_mov_b32_e32 v189, v1
	v_mov_b32_dpp v194, v136 row_ror:15 row_mask:0xf bank_mask:0xf
	v_mov_b32_e32 v196, v1
	v_mov_b32_dpp v195, v137 row_ror:15 row_mask:0xf bank_mask:0xf
	v_mov_b32_e32 v197, v1
	v_mov_b32_dpp v198, v126 row_ror:15 row_mask:0xf bank_mask:0xf
	v_mov_b32_e32 v200, v1
	v_mov_b32_dpp v199, v127 row_ror:15 row_mask:0xf bank_mask:0xf
	v_mov_b32_e32 v201, v1
	v_mov_b32_dpp v190, v128 row_ror:15 row_mask:0xf bank_mask:0xf
	v_mov_b32_e32 v192, v1
	v_mov_b32_dpp v191, v129 row_ror:15 row_mask:0xf bank_mask:0xf
	v_mov_b32_e32 v193, v1
	v_or_b32_e32 v0, v231, v230
	v_mov_b32_dpp v188, v150 row_shr:1 row_mask:0xf bank_mask:0xf
	v_mov_b32_dpp v186, v150 row_shl:1 row_mask:0xf bank_mask:0xf
	v_mov_b32_dpp v189, v151 row_shr:1 row_mask:0xf bank_mask:0xf
	v_mov_b32_dpp v187, v151 row_shl:1 row_mask:0xf bank_mask:0xf
	v_mov_b32_dpp v196, v152 row_shr:1 row_mask:0xf bank_mask:0xf
	v_mov_b32_dpp v194, v152 row_shl:1 row_mask:0xf bank_mask:0xf
	v_mov_b32_dpp v197, v153 row_shr:1 row_mask:0xf bank_mask:0xf
	v_mov_b32_dpp v195, v153 row_shl:1 row_mask:0xf bank_mask:0xf
	v_mov_b32_dpp v200, v142 row_shr:1 row_mask:0xf bank_mask:0xf
	v_mov_b32_dpp v198, v142 row_shl:1 row_mask:0xf bank_mask:0xf
	v_mov_b32_dpp v201, v143 row_shr:1 row_mask:0xf bank_mask:0xf
	v_mov_b32_dpp v199, v143 row_shl:1 row_mask:0xf bank_mask:0xf
	v_mov_b32_dpp v192, v144 row_shr:1 row_mask:0xf bank_mask:0xf
	v_mov_b32_dpp v190, v144 row_shl:1 row_mask:0xf bank_mask:0xf
	v_mov_b32_dpp v193, v145 row_shr:1 row_mask:0xf bank_mask:0xf
	v_mov_b32_dpp v191, v145 row_shl:1 row_mask:0xf bank_mask:0xf
	v_cmp_eq_u32_e64 s[6:7], 0, v230
	v_cmp_ne_u32_e64 s[10:11], 0, v230
	s_and_saveexec_b64 s[8:9], s[10:11]
	s_cbranch_execz .LBB0_59
	s_waitcnt vmcnt(0)
	v_pk_fma_f32 v[200:201], v[66:67], v[200:201], v[78:79]
	v_pk_fma_f32 v[196:197], v[84:85], v[196:197], v[96:97]
	v_pk_fma_f32 v[200:201], v[142:143], v[70:71], v[200:201]
	v_pk_fma_f32 v[196:197], v[152:153], v[88:89], v[196:197]
	v_pk_fma_f32 v[198:199], v[74:75], v[198:199], v[200:201]
	v_pk_fma_f32 v[194:195], v[92:93], v[194:195], v[196:197]
	v_mul_f32_e32 v172, 0xbfb8aa3b, v198
	v_exp_f32_e32 v172, v172
	v_mul_f32_e32 v173, 0xbfb8aa3b, v199
	v_exp_f32_e32 v173, v173
	v_pk_fma_f32 v[188:189], v[82:83], v[188:189], v[94:95]
	v_add_f32_e32 v172, 1.0, v172
	v_rcp_f32_e32 v200, v172
	v_add_f32_e32 v173, 1.0, v173
	v_mul_f32_e32 v172, 0xbfb8aa3b, v194
	v_rcp_f32_e32 v201, v173
	v_exp_f32_e32 v172, v172
	v_mul_f32_e32 v173, 0xbfb8aa3b, v195
	v_exp_f32_e32 v173, v173
	v_pk_mul_f32 v[198:199], v[198:199], v[200:201]
	v_add_f32_e32 v172, 1.0, v172
	v_pk_fma_f32 v[188:189], v[150:151], v[86:87], v[188:189]
	v_pk_mul_f32 v[196:197], v[154:155], v[198:199]
	v_rcp_f32_e32 v198, v172
	v_add_f32_e32 v172, 1.0, v173
	v_pk_fma_f32 v[186:187], v[90:91], v[186:187], v[188:189]
	v_rcp_f32_e32 v199, v172
	v_mul_f32_e32 v172, 0xbfb8aa3b, v186
	v_exp_f32_e32 v172, v172
	v_mul_f32_e32 v173, 0xbfb8aa3b, v187
	v_exp_f32_e32 v173, v173
	v_pk_fma_f32 v[192:193], v[68:69], v[192:193], v[80:81]
	v_add_f32_e32 v172, 1.0, v172
	v_pk_fma_f32 v[192:193], v[144:145], v[72:73], v[192:193]
	v_pk_mul_f32 v[188:189], v[194:195], v[198:199]
	v_pk_fma_f32 v[190:191], v[76:77], v[190:191], v[192:193]
	v_rcp_f32_e32 v194, v172
	v_add_f32_e32 v172, 1.0, v173
	v_mul_f32_e32 v173, 0xbfb8aa3b, v190
	v_exp_f32_e32 v173, v173
	v_mul_f32_e32 v174, 0xbfb8aa3b, v191
	v_exp_f32_e32 v174, v174
	v_rcp_f32_e32 v195, v172
	v_add_f32_e32 v172, 1.0, v173
	v_rcp_f32_e32 v192, v172
	v_add_f32_e32 v172, 1.0, v174
	v_rcp_f32_e32 v193, v172
	v_readlane_b32 s12, v254, 35
	v_readlane_b32 s13, v254, 36
	v_pk_mul_f32 v[186:187], v[186:187], v[194:195]
	v_pk_mul_f32 v[190:191], v[190:191], v[192:193]
	v_mov_b64_e32 v[192:193], s[12:13]
	s_movk_i32 s12, 0x1600
	v_pk_mul_f32 v[188:189], v[160:161], v[188:189]
	v_pk_mul_f32 v[186:187], v[158:159], v[186:187]
	v_pk_mul_f32 v[190:191], v[156:157], v[190:191]
	v_mad_i64_i32 v[192:193], s[12:13], v0, s12, v[192:193]
	v_lshl_add_u64 v[192:193], v[184:185], 1, v[192:193]
	v_cvt_pk_bf16_f32 v186, v186, v187
	v_cvt_pk_bf16_f32 v187, v188, v189
	v_cvt_pk_bf16_f32 v188, v196, v197
	v_cvt_pk_bf16_f32 v189, v190, v191
	global_store_dwordx4 v[192:193], v[186:189], off

.LBB0_67:
	s_or_b64 exec, exec, s[40:41]
	s_cmp_lg_u32 s99, 0
	s_cbranch_scc1 .LBB0_52
	v_mov_b32_e32 v98, v1
	v_mov_b32_e32 v99, v1
	v_mov_b32_e32 v106, v1
	v_mov_b32_e32 v107, v1
	v_mov_b32_e32 v110, v1
	v_mov_b32_e32 v111, v1
	v_mov_b32_e32 v102, v1
	v_mov_b32_e32 v103, v1
	v_add_u32_e32 v115, 0x80, v231
	v_mov_b32_dpp v98, v38 row_ror:15 row_mask:0xf bank_mask:0xf
	v_mov_b32_e32 v100, v1
	v_mov_b32_dpp v99, v39 row_ror:15 row_mask:0xf bank_mask:0xf
	v_mov_b32_e32 v101, v1
	v_mov_b32_dpp v106, v40 row_ror:15 row_mask:0xf bank_mask:0xf
	v_mov_b32_e32 v108, v1
	v_mov_b32_dpp v107, v41 row_ror:15 row_mask:0xf bank_mask:0xf
	v_mov_b32_e32 v109, v1
	v_mov_b32_dpp v110, v30 row_ror:15 row_mask:0xf bank_mask:0xf
	v_mov_b32_e32 v112, v1
	v_mov_b32_dpp v111, v31 row_ror:15 row_mask:0xf bank_mask:0xf
	v_mov_b32_e32 v113, v1
	v_mov_b32_dpp v102, v32 row_ror:15 row_mask:0xf bank_mask:0xf
	v_mov_b32_e32 v104, v1
	v_mov_b32_dpp v103, v33 row_ror:15 row_mask:0xf bank_mask:0xf
	v_mov_b32_e32 v105, v1
	v_or_b32_e32 v114, v115, v230
	v_mov_b32_dpp v100, v54 row_shr:1 row_mask:0xf bank_mask:0xf
	v_mov_b32_dpp v98, v54 row_shl:1 row_mask:0xf bank_mask:0xf
	v_mov_b32_dpp v101, v55 row_shr:1 row_mask:0xf bank_mask:0xf
	v_mov_b32_dpp v99, v55 row_shl:1 row_mask:0xf bank_mask:0xf
	v_mov_b32_dpp v108, v56 row_shr:1 row_mask:0xf bank_mask:0xf
	v_mov_b32_dpp v106, v56 row_shl:1 row_mask:0xf bank_mask:0xf
	v_mov_b32_dpp v109, v57 row_shr:1 row_mask:0xf bank_mask:0xf
	v_mov_b32_dpp v107, v57 row_shl:1 row_mask:0xf bank_mask:0xf
	v_mov_b32_dpp v112, v46 row_shr:1 row_mask:0xf bank_mask:0xf
	v_mov_b32_dpp v110, v46 row_shl:1 row_mask:0xf bank_mask:0xf
	v_mov_b32_dpp v113, v47 row_shr:1 row_mask:0xf bank_mask:0xf
	v_mov_b32_dpp v111, v47 row_shl:1 row_mask:0xf bank_mask:0xf
	v_mov_b32_dpp v104, v48 row_shr:1 row_mask:0xf bank_mask:0xf
	v_mov_b32_dpp v102, v48 row_shl:1 row_mask:0xf bank_mask:0xf
	v_mov_b32_dpp v105, v49 row_shr:1 row_mask:0xf bank_mask:0xf
	v_mov_b32_dpp v103, v49 row_shl:1 row_mask:0xf bank_mask:0xf
	s_and_saveexec_b64 s[40:41], s[10:11]
	s_cbranch_execz .LBB0_69
	v_pk_fma_f32 v[112:113], v[66:67], v[112:113], v[78:79]
	v_pk_fma_f32 v[108:109], v[84:85], v[108:109], v[96:97]
	v_pk_fma_f32 v[112:113], v[46:47], v[70:71], v[112:113]
	v_pk_fma_f32 v[108:109], v[56:57], v[88:89], v[108:109]
	v_pk_fma_f32 v[110:111], v[74:75], v[110:111], v[112:113]
	v_pk_fma_f32 v[106:107], v[92:93], v[106:107], v[108:109]
	v_mul_f32_e32 v112, 0xbfb8aa3b, v110
	v_mul_f32_e32 v113, 0xbfb8aa3b, v111
	v_exp_f32_e32 v112, v112
	v_exp_f32_e32 v113, v113
	v_mul_f32_e32 v108, 0xbfb8aa3b, v106
	v_pk_fma_f32 v[100:101], v[82:83], v[100:101], v[94:95]
	v_add_f32_e32 v112, 1.0, v112
	v_add_f32_e32 v113, 1.0, v113
	v_rcp_f32_e32 v112, v112
	v_rcp_f32_e32 v113, v113
	v_pk_fma_f32 v[100:101], v[54:55], v[86:87], v[100:101]
	v_pk_fma_f32 v[104:105], v[68:69], v[104:105], v[80:81]
	v_pk_fma_f32 v[98:99], v[90:91], v[98:99], v[100:101]
	v_pk_mul_f32 v[110:111], v[110:111], v[112:113]
	v_exp_f32_e32 v112, v108
	v_mul_f32_e32 v108, 0xbfb8aa3b, v107
	v_exp_f32_e32 v113, v108
	v_pk_fma_f32 v[104:105], v[48:49], v[72:73], v[104:105]
	v_mul_f32_e32 v100, 0xbfb8aa3b, v98
	v_pk_fma_f32 v[102:103], v[76:77], v[102:103], v[104:105]
	v_pk_mul_f32 v[108:109], v[58:59], v[110:111]
	v_add_f32_e32 v110, 1.0, v112
	v_add_f32_e32 v111, 1.0, v113
	v_exp_f32_e32 v112, v100
	v_mul_f32_e32 v100, 0xbfb8aa3b, v99
	v_mul_f32_e32 v104, 0xbfb8aa3b, v102
	v_mul_f32_e32 v105, 0xbfb8aa3b, v103
	v_rcp_f32_e32 v110, v110
	v_rcp_f32_e32 v111, v111
	v_exp_f32_e32 v113, v100
	v_exp_f32_e32 v104, v104
	v_exp_f32_e32 v105, v105
	v_pk_mul_f32 v[100:101], v[106:107], v[110:111]
	v_add_f32_e32 v106, 1.0, v112
	v_add_f32_e32 v107, 1.0, v113
	v_add_f32_e32 v104, 1.0, v104
	v_add_f32_e32 v105, 1.0, v105
	v_rcp_f32_e32 v106, v106
	v_rcp_f32_e32 v107, v107
	v_rcp_f32_e32 v104, v104
	v_rcp_f32_e32 v105, v105
	v_readlane_b32 s10, v254, 35
	v_readlane_b32 s11, v254, 36
	v_pk_mul_f32 v[98:99], v[98:99], v[106:107]
	v_pk_mul_f32 v[102:103], v[102:103], v[104:105]
	v_mov_b64_e32 v[104:105], s[10:11]
	v_pk_mul_f32 v[100:101], v[64:65], v[100:101]
	v_pk_mul_f32 v[98:99], v[62:63], v[98:99]
	v_pk_mul_f32 v[102:103], v[60:61], v[102:103]
	v_mad_i64_i32 v[104:105], s[10:11], v114, s25, v[104:105]
	v_lshl_add_u64 v[104:105], v[184:185], 1, v[104:105]
	v_cvt_pk_bf16_f32 v98, v98, v99
	v_cvt_pk_bf16_f32 v99, v100, v101
	v_cvt_pk_bf16_f32 v100, v108, v109
	v_cvt_pk_bf16_f32 v101, v102, v103
	global_store_dwordx4 v[104:105], v[98:101], off

.LBB0_83:
	v_readlane_b32 s98, v255, 41
	s_cmp_lg_u32 s98, 0
	s_cselect_b32 s0, 0x80, s0
	v_readlane_b32 s1, v254, 0
	s_cmp_lt_i32 s1, s0
	s_mov_b64 s[4:5], -1
	s_cbranch_scc1 .LBB0_181
	v_readlane_b32 s1, v254, 0
	v_readlane_b32 s2, v254, 5
	s_sub_i32 s1, s1, s0
	s_sub_i32 s2, s2, s0
	v_mov_b32_e32 v0, v163
	s_cmpk_gt_i32 s1, 0x27f
	s_mov_b32 s10, s1
	s_cbranch_scc1 .LBB0_123
	v_readlane_b32 s6, v254, 25
	v_readlane_b32 s7, v254, 26
	s_load_dwordx2 s[4:5], s[6:7], 0x78
	v_and_b32_e32 v6, 63, v0
	s_load_dwordx2 s[6:7], s[6:7], 0x118
	v_ashrrev_i32_e32 v7, 6, v0
	v_lshlrev_b32_e32 v0, 1, v6
	v_lshl_add_u32 v4, v6, 2, 0
	v_lshlrev_b32_e32 v5, 8, v6
	s_waitcnt lgkmcnt(0)
	v_lshl_add_u64 v[2:3], s[6:7], 0, v[0:1]
	s_mov_b64 s[6:7], 0x74000
	v_lshl_add_u64 v[2:3], v[2:3], 0, s[6:7]
	s_movk_i32 s6, 0x104
	s_add_u32 s4, s4, 0x9b0000
	v_mul_lo_u32 v0, v7, s6
	v_lshlrev_b32_e32 v15, 2, v7
	s_addc_u32 s5, s5, 0
	s_lshl_b32 s3, s2, 1
	v_add_u32_e32 v8, 8, v7
	v_add_u32_e32 v9, 16, v7
	v_add_u32_e32 v10, 24, v7
	v_add_u32_e32 v11, 32, v7
	v_add_u32_e32 v12, 40, v7
	v_add_u32_e32 v13, 48, v7
	v_add_u32_e32 v14, 56, v7
	v_add3_u32 v15, v4, v5, v15
	s_lshl_b32 s11, s1, 6
	s_lshl_b32 s12, s2, 7
	v_add_u32_e32 v16, v4, v0
	s_mov_b32 s10, s1
	s_branch .LBB0_87

.LBB0_1242:
	v_cndmask_b32_e64 v2, 0, 1, s[6:7]
	v_cmp_ne_u32_e64 s[8:9], 1, v2
	s_andn2_b64 vcc, exec, s[6:7]
	s_mov_b64 s[6:7], s[14:15]
	s_cbranch_vccnz .LBB0_1244
	s_mul_i32 s6, s38, 0x160000
	v_readlane_b32 s18, v254, 35
	s_mul_hi_i32 s7, s38, 0x160000
	v_readlane_b32 s19, v254, 36
	s_add_u32 s6, s18, s6
	s_addc_u32 s7, s19, s7
	v_readlane_b32 s98, v254, 0
	s_and_b32 s98, s98, s99
	s_mul_i32 s98, s98, 0xb0000
	s_add_u32 s6, s6, s98
	s_addc_u32 s7, s7, 0
